# background work queue: store drain (vmcnt 0) before the ticket atomic removed, the ticket fetch overlaps the previous item stores
# baseline (speedup 1.0000x reference)
; DI unsigned xb_add(unsigned* p, unsigned v) { return __hip_atomic_fetch_add(p, v, __ATOMIC_RELAXED, __HIP_MEMORY_SCOPE_AGENT); }
; DI void drain_bg(const Params& P, unsigned char* lds, const int wv, const int lnext, const int which) {
;     ...
;   for (;;) {
;     const int tid = get_tid(wv);
;     __syncthreads();
;     if (tid == 0) *slot = (int)xb_add(ctr, 1u);
;     __syncthreads();
;     const int it = *slot;
.LBB0_1025:
	v_mbcnt_lo_u32_b32 v56, -1, 0
	v_mbcnt_hi_u32_b32 v56, -1, v56
	v_or_b32 v56, s90, v56
	v_cmp_eq_u32_e32 vcc, 0, v56
	s_barrier
	s_and_saveexec_b64 s[0:1], vcc
	s_cbranch_execz .LBB0_1029
	s_mov_b64 s[4:5], exec
	v_mbcnt_lo_u32_b32 v0, s4, 0
	v_mbcnt_hi_u32_b32 v0, s5, v0
	v_cmp_eq_u32_e32 vcc, 0, v0
	s_and_saveexec_b64 s[2:3], vcc
	s_cbranch_execz .LBB0_1028
	s_bcnt1_i32_b64 s4, s[4:5]
	v_mov_b32_e32 v2, s4
	global_atomic_add v2, v[54:55], v2, off sc0
